# grid barrier: each workgroup issues its acquire invalidate right after its arrival atomic (runs while it waits) instead of after the release; waits unchanged
# speedup vs baseline: 1.0131x; 1.0131x over previous
.LBB0_173:
	s_lshl_b32 s8, s3, 8
	s_add_u32 s8, s40, s8
	s_addc_u32 s9, s41, 0
	v_mov_b32_e32 v2, 0x1000
	v_mov_b32_e32 v4, 1
	global_atomic_add v4, v2, v4, s[8:9] offset:1024 sc0
	buffer_inv sc1
	v_cvt_f32_u32_e32 v2, v3
	v_sub_u32_e32 v5, 0, v3
	v_rcp_iflag_f32_e32 v2, v2
	s_nop 0
	v_mul_f32_e32 v2, 0x4f7ffffe, v2
	v_cvt_u32_f32_e32 v2, v2
	v_mul_lo_u32 v5, v5, v2
	v_mul_hi_u32 v5, v2, v5
	v_add_u32_e32 v2, v2, v5
	s_waitcnt vmcnt(1)
	v_mul_hi_u32 v2, v4, v2
	v_mul_lo_u32 v5, v2, v3
	v_sub_u32_e32 v5, v4, v5
	v_add_u32_e32 v6, 1, v2
	v_cmp_ge_u32_e32 vcc, v5, v3
	v_add_u32_e32 v4, 1, v4
	s_nop 0
	v_cndmask_b32_e32 v2, v2, v6, vcc
	v_sub_u32_e32 v6, v5, v3
	v_cndmask_b32_e32 v5, v5, v6, vcc
	v_add_u32_e32 v6, 1, v2
	v_cmp_ge_u32_e32 vcc, v5, v3
	s_nop 1
	v_cndmask_b32_e32 v2, v2, v6, vcc
	v_mul_lo_u32 v5, v3, v2
	v_add_u32_e32 v3, v5, v3
	v_cmp_ne_u32_e32 vcc, v4, v3
	s_and_saveexec_b64 s[10:11], vcc
	s_xor_b64 s[10:11], exec, s[10:11]
	s_cbranch_execz .LBB0_187
	s_waitcnt lgkmcnt(0)
	v_add_u32_e32 v5, 1, v2
	v_mul_lo_u32 v5, v5, v1
	v_mov_b32_e32 v1, 0x7400
	global_load_dword v1, v1, s[38:39] sc1
	s_add_u32 s18, s38, 0x7400
	s_addc_u32 s19, s39, 0
	s_waitcnt vmcnt(0)
	v_cmp_lt_u32_e32 vcc, v1, v5
	s_and_saveexec_b64 s[12:13], vcc
	s_cbranch_execz .LBB0_186
	s_add_u32 s14, s38, 0x4200
	s_addc_u32 s15, s39, 0
	s_mov_b32 s46, 1
	s_mov_b64 s[20:21], 0
	v_mov_b32_e32 v1, 0
	s_branch .LBB0_177

.LBB0_186:
	s_or_b64 exec, exec, s[12:13]
	s_waitcnt vmcnt(0)
	s_waitcnt vmcnt(0)

.LBB0_815:
	s_lshl_b32 s4, s3, 8
	s_add_u32 s4, s40, s4
	s_addc_u32 s5, s41, 0
	v_mov_b32_e32 v2, 0x1000
	v_mov_b32_e32 v4, 1
	global_atomic_add v4, v2, v4, s[4:5] offset:1024 sc0
	buffer_inv sc1
	v_cvt_f32_u32_e32 v2, v3
	v_sub_u32_e32 v5, 0, v3
	v_rcp_iflag_f32_e32 v2, v2
	s_nop 0
	v_mul_f32_e32 v2, 0x4f7ffffe, v2
	v_cvt_u32_f32_e32 v2, v2
	v_mul_lo_u32 v5, v5, v2
	v_mul_hi_u32 v5, v2, v5
	v_add_u32_e32 v2, v2, v5
	s_waitcnt vmcnt(1)
	v_mul_hi_u32 v2, v4, v2
	v_mul_lo_u32 v5, v2, v3
	v_sub_u32_e32 v5, v4, v5
	v_add_u32_e32 v6, 1, v2
	v_cmp_ge_u32_e32 vcc, v5, v3
	v_add_u32_e32 v4, 1, v4
	s_nop 0
	v_cndmask_b32_e32 v2, v2, v6, vcc
	v_sub_u32_e32 v6, v5, v3
	v_cndmask_b32_e32 v5, v5, v6, vcc
	v_add_u32_e32 v6, 1, v2
	v_cmp_ge_u32_e32 vcc, v5, v3
	s_nop 1
	v_cndmask_b32_e32 v2, v2, v6, vcc
	v_mul_lo_u32 v5, v3, v2
	v_add_u32_e32 v3, v5, v3
	v_cmp_ne_u32_e32 vcc, v4, v3
	s_and_saveexec_b64 s[6:7], vcc
	s_xor_b64 s[6:7], exec, s[6:7]
	s_cbranch_execz .LBB0_829
	s_waitcnt lgkmcnt(0)
	v_add_u32_e32 v5, 1, v2
	v_mul_lo_u32 v5, v5, v1
	v_mov_b32_e32 v1, 0x7400
	global_load_dword v1, v1, s[38:39] sc1
	s_add_u32 s12, s38, 0x7400
	s_addc_u32 s13, s39, 0
	s_waitcnt vmcnt(0)
	v_cmp_lt_u32_e32 vcc, v1, v5
	s_and_saveexec_b64 s[8:9], vcc
	s_cbranch_execz .LBB0_828
	s_add_u32 s10, s38, 0x4200
	s_addc_u32 s11, s39, 0
	s_mov_b32 s26, 1
	s_mov_b64 s[14:15], 0
	v_mov_b32_e32 v1, 0
	s_branch .LBB0_819

.LBB0_828:
	s_or_b64 exec, exec, s[8:9]
	s_waitcnt vmcnt(0)
	s_waitcnt vmcnt(0)

.LBB0_899:
	s_lshl_b32 s6, s3, 8
	s_add_u32 s6, s40, s6
	s_addc_u32 s7, s41, 0
	v_mov_b32_e32 v2, 0x1000
	v_mov_b32_e32 v4, 1
	global_atomic_add v4, v2, v4, s[6:7] offset:1024 sc0
	buffer_inv sc1
	v_cvt_f32_u32_e32 v2, v3
	v_sub_u32_e32 v5, 0, v3
	v_rcp_iflag_f32_e32 v2, v2
	s_nop 0
	v_mul_f32_e32 v2, 0x4f7ffffe, v2
	v_cvt_u32_f32_e32 v2, v2
	v_mul_lo_u32 v5, v5, v2
	v_mul_hi_u32 v5, v2, v5
	v_add_u32_e32 v2, v2, v5
	s_waitcnt vmcnt(1)
	v_mul_hi_u32 v2, v4, v2
	v_mul_lo_u32 v5, v2, v3
	v_sub_u32_e32 v5, v4, v5
	v_add_u32_e32 v6, 1, v2
	v_cmp_ge_u32_e32 vcc, v5, v3
	v_add_u32_e32 v4, 1, v4
	s_nop 0
	v_cndmask_b32_e32 v2, v2, v6, vcc
	v_sub_u32_e32 v6, v5, v3
	v_cndmask_b32_e32 v5, v5, v6, vcc
	v_add_u32_e32 v6, 1, v2
	v_cmp_ge_u32_e32 vcc, v5, v3
	s_nop 1
	v_cndmask_b32_e32 v2, v2, v6, vcc
	v_mul_lo_u32 v5, v3, v2
	v_add_u32_e32 v3, v5, v3
	v_cmp_ne_u32_e32 vcc, v4, v3
	s_and_saveexec_b64 s[8:9], vcc
	s_xor_b64 s[8:9], exec, s[8:9]
	s_cbranch_execz .LBB0_913
	s_waitcnt lgkmcnt(0)
	v_add_u32_e32 v5, 1, v2
	v_mul_lo_u32 v5, v5, v1
	v_mov_b32_e32 v1, 0x7400
	global_load_dword v1, v1, s[38:39] sc1
	s_add_u32 s14, s38, 0x7400
	s_addc_u32 s15, s39, 0
	s_waitcnt vmcnt(0)
	v_cmp_lt_u32_e32 vcc, v1, v5
	s_and_saveexec_b64 s[10:11], vcc
	s_cbranch_execz .LBB0_912
	s_add_u32 s12, s38, 0x4200
	s_addc_u32 s13, s39, 0
	s_mov_b32 s26, 1
	s_mov_b64 s[16:17], 0
	v_mov_b32_e32 v1, 0
	s_branch .LBB0_903

.LBB0_912:
	s_or_b64 exec, exec, s[10:11]
	s_waitcnt vmcnt(0)
	s_waitcnt vmcnt(0)

.LBB0_1150:
	s_lshl_b32 s3, s3, 8
	s_add_u32 s6, s40, s3
	s_addc_u32 s7, s41, 0
	v_mov_b32_e32 v2, 0x1000
	v_mov_b32_e32 v4, 1
	global_atomic_add v4, v2, v4, s[6:7] offset:1024 sc0
	buffer_inv sc1
	v_cvt_f32_u32_e32 v2, v3
	v_sub_u32_e32 v5, 0, v3
	v_rcp_iflag_f32_e32 v2, v2
	s_nop 0
	v_mul_f32_e32 v2, 0x4f7ffffe, v2
	v_cvt_u32_f32_e32 v2, v2
	v_mul_lo_u32 v5, v5, v2
	v_mul_hi_u32 v5, v2, v5
	v_add_u32_e32 v2, v2, v5
	s_waitcnt vmcnt(1)
	v_mul_hi_u32 v2, v4, v2
	v_mul_lo_u32 v5, v2, v3
	v_sub_u32_e32 v5, v4, v5
	v_add_u32_e32 v6, 1, v2
	v_cmp_ge_u32_e32 vcc, v5, v3
	v_add_u32_e32 v4, 1, v4
	s_nop 0
	v_cndmask_b32_e32 v2, v2, v6, vcc
	v_sub_u32_e32 v6, v5, v3
	v_cndmask_b32_e32 v5, v5, v6, vcc
	v_add_u32_e32 v6, 1, v2
	v_cmp_ge_u32_e32 vcc, v5, v3
	s_nop 1
	v_cndmask_b32_e32 v2, v2, v6, vcc
	v_mul_lo_u32 v5, v3, v2
	v_add_u32_e32 v3, v5, v3
	v_cmp_ne_u32_e32 vcc, v4, v3
	s_and_saveexec_b64 s[8:9], vcc
	s_xor_b64 s[8:9], exec, s[8:9]
	s_cbranch_execz .LBB0_1164
	s_waitcnt lgkmcnt(0)
	v_add_u32_e32 v5, 1, v2
	v_mul_lo_u32 v5, v5, v1
	v_mov_b32_e32 v1, 0x7400
	global_load_dword v1, v1, s[38:39] sc1
	s_add_u32 s14, s38, 0x7400
	s_addc_u32 s15, s39, 0
	s_waitcnt vmcnt(0)
	v_cmp_lt_u32_e32 vcc, v1, v5
	s_and_saveexec_b64 s[10:11], vcc
	s_cbranch_execz .LBB0_1163
	s_add_u32 s12, s38, 0x4200
	s_addc_u32 s13, s39, 0
	s_mov_b32 s3, 1
	s_mov_b64 s[16:17], 0
	v_mov_b32_e32 v1, 0
	s_branch .LBB0_1154
